# waits to first consumer: attention A odd step - exp2 of the first score block issued before the DMA-arrival vmcnt wait instead of after it
# speedup vs baseline: 1.0084x; 1.0084x over previous
; template <bool FIRST> __device__ __forceinline__ void partialSM(f32x16& p0, f32x16& p1, float& m_reg, f32x16& negm, float& alpha) {
;     ...
;   if (FIRST || __builtin_expect(__any(pmax > THR), 0)) { const float dl = FIRST ? pmax : fmaxf(pmax, 0.f); m_reg += dl; if (!FIRST) alpha = __builtin_amdgcn_exp2f(-dl);
; #pragma unroll
;     for (int r = 0; r < 16; ++r) { p0[r] -= dl; p1[r] -= dl; }
; #pragma unroll
;     for (int r = 0; r < 16; ++r) negm[r] = -m_reg; }
; #pragma unroll
;   for (int r = 0; r < 16; ++r) p0[r] = __builtin_amdgcn_exp2f(p0[r]);
.LBB0_209:
	v_exp_f32_e32 v172, v128
	v_exp_f32_e32 v174, v129
	v_exp_f32_e32 v175, v130
	v_exp_f32_e32 v211, v131
	v_exp_f32_e32 v212, v132
	v_exp_f32_e32 v215, v133
	v_exp_f32_e32 v216, v134
	v_exp_f32_e32 v233, v135
	v_exp_f32_e32 v173, v136
	v_exp_f32_e32 v176, v137
	v_exp_f32_e32 v177, v138
	v_exp_f32_e32 v213, v139
	v_exp_f32_e32 v214, v140
	v_exp_f32_e32 v217, v141
	v_exp_f32_e32 v232, v142
	v_exp_f32_e32 v234, v143
	s_mov_b64 s[54:55], -1
	s_and_b64 vcc, exec, s[52:53]
	s_cbranch_vccz .LBB0_211
	s_waitcnt vmcnt(0) lgkmcnt(0)
	s_mov_b64 s[54:55], 0
